# GEMM1 plain epilogue: q-scale chosen once as a scalar (scale or exact 1.0) and applied in place; 128 per-element v_cndmask per tile removed
# baseline (speedup 1.0000x reference)
; __device__ __forceinline__ unsigned cvt_pk_bf16(float lo, float hi) { const f32x2c_t v = {lo, hi}; const bf16x2c_t b = __builtin_convertvector(v, bf16x2c_t); return __builtin_bit_cast(unsigned, b); }
;     __device__ __forceinline__ void operator()(const f32x4 (&acc)[2][2][4][2], const Unit& u, int wr, int wc, int fr, int fq) const {
;     ...
;         const bool qs = u.pn < 6;
; #pragma unroll
;         for (int ai = 0; ai < 2; ++ai)
; #pragma unroll
;             for (int m = 0; m < 4; ++m) { bf16_t* rowp = Z + (size_t)(row0 + ai * HALF + m * 16) * DIN + col0;
; #pragma unroll
;                 for (int bj = 0; bj < 2; ++bj) { f32x4 v0 = acc[ai][bj][m][0], v1 = acc[ai][bj][m][1];
;                     if (qs) { v0 = v0 * QSCALE; v1 = v1 * QSCALE; }
;                     u32x4 w; w.x = cvt_pk_bf16(v0[0], v0[1]); w.y = cvt_pk_bf16(v0[2], v0[3]); w.z = cvt_pk_bf16(v1[0], v1[1]); w.w = cvt_pk_bf16(v1[2], v1[3]);
;                     *(u32x4*)(rowp + bj * HALF) = w; } }
.LBB0_287:
	v_lshl_or_b32 v158, s57, 8, v161
	v_lshl_add_u32 v163, s58, 8, v1
	v_ashrrev_i32_e32 v159, 31, v158
	v_mov_b64_e32 v[156:157], s[92:93]
	s_cmp_lt_i32 s57, 6
	s_cselect_b32 vcc_lo, s48, 1.0
	v_mad_i64_i32 v[164:165], s[18:19], v163, s27, v[156:157]
	v_lshlrev_b64 v[158:159], 1, v[158:159]
	v_lshl_add_u64 v[168:169], v[164:165], 0, v[158:159]
	v_pk_mul_f32 v[128:129], v[128:129], vcc op_sel_hi:[1,0]
	v_pk_mul_f32 v[126:127], v[126:127], vcc op_sel_hi:[1,0]
	v_pk_mul_f32 v[124:125], v[124:125], vcc op_sel_hi:[1,0]
	v_pk_mul_f32 v[122:123], v[122:123], vcc op_sel_hi:[1,0]
	v_cvt_pk_bf16_f32 v164, v126, v127
	v_cvt_pk_bf16_f32 v165, v128, v129
	v_cvt_pk_bf16_f32 v166, v122, v123
	v_cvt_pk_bf16_f32 v167, v124, v125
	global_store_dwordx4 v[168:169], v[164:167], off
	v_pk_mul_f32 v[116:117], v[116:117], vcc op_sel_hi:[1,0]
	v_pk_mul_f32 v[114:115], v[114:115], vcc op_sel_hi:[1,0]
	v_pk_mul_f32 v[120:121], v[120:121], vcc op_sel_hi:[1,0]
	v_pk_mul_f32 v[118:119], v[118:119], vcc op_sel_hi:[1,0]
	v_cvt_pk_bf16_f32 v164, v118, v119
	v_cvt_pk_bf16_f32 v165, v120, v121
	v_cvt_pk_bf16_f32 v166, v114, v115
	v_cvt_pk_bf16_f32 v167, v116, v117
	global_store_dwordx4 v[168:169], v[164:167], off offset:256
	v_pk_mul_f32 v[108:109], v[108:109], vcc op_sel_hi:[1,0]
	v_pk_mul_f32 v[106:107], v[106:107], vcc op_sel_hi:[1,0]
	v_or_b32_e32 v164, 16, v163
	v_mad_i64_i32 v[164:165], s[18:19], v164, s27, v[156:157]
	v_lshl_add_u64 v[168:169], v[164:165], 0, v[158:159]
	v_pk_mul_f32 v[112:113], v[112:113], vcc op_sel_hi:[1,0]
	v_pk_mul_f32 v[110:111], v[110:111], vcc op_sel_hi:[1,0]
	v_cvt_pk_bf16_f32 v164, v110, v111
	v_cvt_pk_bf16_f32 v165, v112, v113
	v_cvt_pk_bf16_f32 v166, v106, v107
	v_cvt_pk_bf16_f32 v167, v108, v109
	global_store_dwordx4 v[168:169], v[164:167], off
	v_pk_mul_f32 v[100:101], v[100:101], vcc op_sel_hi:[1,0]
	v_pk_mul_f32 v[98:99], v[98:99], vcc op_sel_hi:[1,0]
	v_pk_mul_f32 v[104:105], v[104:105], vcc op_sel_hi:[1,0]
	v_pk_mul_f32 v[102:103], v[102:103], vcc op_sel_hi:[1,0]
	v_cvt_pk_bf16_f32 v164, v102, v103
	v_cvt_pk_bf16_f32 v165, v104, v105
	v_cvt_pk_bf16_f32 v166, v98, v99
	v_cvt_pk_bf16_f32 v167, v100, v101
	global_store_dwordx4 v[168:169], v[164:167], off offset:256
	v_pk_mul_f32 v[92:93], v[92:93], vcc op_sel_hi:[1,0]
	v_pk_mul_f32 v[90:91], v[90:91], vcc op_sel_hi:[1,0]
	v_or_b32_e32 v164, 32, v163
	v_mad_i64_i32 v[164:165], s[18:19], v164, s27, v[156:157]
	v_lshl_add_u64 v[168:169], v[164:165], 0, v[158:159]
	v_pk_mul_f32 v[96:97], v[96:97], vcc op_sel_hi:[1,0]
	v_pk_mul_f32 v[94:95], v[94:95], vcc op_sel_hi:[1,0]
	v_cvt_pk_bf16_f32 v164, v94, v95
	v_cvt_pk_bf16_f32 v165, v96, v97
	v_cvt_pk_bf16_f32 v166, v90, v91
	v_cvt_pk_bf16_f32 v167, v92, v93
	global_store_dwordx4 v[168:169], v[164:167], off
	v_pk_mul_f32 v[84:85], v[84:85], vcc op_sel_hi:[1,0]
	v_pk_mul_f32 v[82:83], v[82:83], vcc op_sel_hi:[1,0]
	v_pk_mul_f32 v[88:89], v[88:89], vcc op_sel_hi:[1,0]
	v_pk_mul_f32 v[86:87], v[86:87], vcc op_sel_hi:[1,0]
	v_cvt_pk_bf16_f32 v164, v86, v87
	v_cvt_pk_bf16_f32 v165, v88, v89
	v_cvt_pk_bf16_f32 v166, v82, v83
	v_cvt_pk_bf16_f32 v167, v84, v85
	global_store_dwordx4 v[168:169], v[164:167], off offset:256
	v_pk_mul_f32 v[76:77], v[76:77], vcc op_sel_hi:[1,0]
	v_pk_mul_f32 v[74:75], v[74:75], vcc op_sel_hi:[1,0]
	v_or_b32_e32 v164, 48, v163
	v_mad_i64_i32 v[164:165], s[18:19], v164, s27, v[156:157]
	v_lshl_add_u64 v[168:169], v[164:165], 0, v[158:159]
	v_pk_mul_f32 v[80:81], v[80:81], vcc op_sel_hi:[1,0]
	v_pk_mul_f32 v[78:79], v[78:79], vcc op_sel_hi:[1,0]
	v_cvt_pk_bf16_f32 v164, v78, v79
	v_cvt_pk_bf16_f32 v165, v80, v81
	v_cvt_pk_bf16_f32 v166, v74, v75
	v_cvt_pk_bf16_f32 v167, v76, v77
	global_store_dwordx4 v[168:169], v[164:167], off
	v_pk_mul_f32 v[68:69], v[68:69], vcc op_sel_hi:[1,0]
	v_pk_mul_f32 v[66:67], v[66:67], vcc op_sel_hi:[1,0]
	v_pk_mul_f32 v[72:73], v[72:73], vcc op_sel_hi:[1,0]
	v_pk_mul_f32 v[70:71], v[70:71], vcc op_sel_hi:[1,0]
	v_cvt_pk_bf16_f32 v164, v70, v71
	v_cvt_pk_bf16_f32 v165, v72, v73
; __device__ __forceinline__ unsigned cvt_pk_bf16(float lo, float hi) { const f32x2c_t v = {lo, hi}; const bf16x2c_t b = __builtin_convertvector(v, bf16x2c_t); return __builtin_bit_cast(unsigned, b); }
;     __device__ __forceinline__ void operator()(const f32x4 (&acc)[2][2][4][2], const Unit& u, int wr, int wc, int fr, int fq) const {
;     ...
;         const bool qs = u.pn < 6;
; #pragma unroll
;         for (int ai = 0; ai < 2; ++ai)
; #pragma unroll
;             for (int m = 0; m < 4; ++m) { bf16_t* rowp = Z + (size_t)(row0 + ai * HALF + m * 16) * DIN + col0;
; #pragma unroll
;                 for (int bj = 0; bj < 2; ++bj) { f32x4 v0 = acc[ai][bj][m][0], v1 = acc[ai][bj][m][1];
;                     if (qs) { v0 = v0 * QSCALE; v1 = v1 * QSCALE; }
;                     u32x4 w; w.x = cvt_pk_bf16(v0[0], v0[1]); w.y = cvt_pk_bf16(v0[2], v0[3]); w.z = cvt_pk_bf16(v1[0], v1[1]); w.w = cvt_pk_bf16(v1[2], v1[3]);
;                     *(u32x4*)(rowp + bj * HALF) = w; } }
	v_cvt_pk_bf16_f32 v166, v66, v67
	v_cvt_pk_bf16_f32 v167, v68, v69
	global_store_dwordx4 v[168:169], v[164:167], off offset:256
	v_pk_mul_f32 v[60:61], v[60:61], vcc op_sel_hi:[1,0]
	v_pk_mul_f32 v[58:59], v[58:59], vcc op_sel_hi:[1,0]
	v_add_u32_e32 v164, 0x80, v163
	v_mad_i64_i32 v[164:165], s[18:19], v164, s27, v[156:157]
	v_lshl_add_u64 v[168:169], v[164:165], 0, v[158:159]
	v_pk_mul_f32 v[64:65], v[64:65], vcc op_sel_hi:[1,0]
	v_pk_mul_f32 v[62:63], v[62:63], vcc op_sel_hi:[1,0]
	v_cvt_pk_bf16_f32 v164, v62, v63
	v_cvt_pk_bf16_f32 v165, v64, v65
	v_cvt_pk_bf16_f32 v166, v58, v59
	v_cvt_pk_bf16_f32 v167, v60, v61
	global_store_dwordx4 v[168:169], v[164:167], off
	v_pk_mul_f32 v[52:53], v[52:53], vcc op_sel_hi:[1,0]
	v_pk_mul_f32 v[50:51], v[50:51], vcc op_sel_hi:[1,0]
	v_pk_mul_f32 v[56:57], v[56:57], vcc op_sel_hi:[1,0]
	v_pk_mul_f32 v[54:55], v[54:55], vcc op_sel_hi:[1,0]
	v_cvt_pk_bf16_f32 v164, v54, v55
	v_cvt_pk_bf16_f32 v165, v56, v57
	v_cvt_pk_bf16_f32 v166, v50, v51
	v_cvt_pk_bf16_f32 v167, v52, v53
	global_store_dwordx4 v[168:169], v[164:167], off offset:256
	v_pk_mul_f32 v[44:45], v[44:45], vcc op_sel_hi:[1,0]
	v_pk_mul_f32 v[42:43], v[42:43], vcc op_sel_hi:[1,0]
	v_add_u32_e32 v164, 0x90, v163
	v_mad_i64_i32 v[164:165], s[18:19], v164, s27, v[156:157]
	v_lshl_add_u64 v[168:169], v[164:165], 0, v[158:159]
	v_pk_mul_f32 v[48:49], v[48:49], vcc op_sel_hi:[1,0]
	v_pk_mul_f32 v[46:47], v[46:47], vcc op_sel_hi:[1,0]
	v_cvt_pk_bf16_f32 v164, v46, v47
	v_cvt_pk_bf16_f32 v165, v48, v49
	v_cvt_pk_bf16_f32 v166, v42, v43
	v_cvt_pk_bf16_f32 v167, v44, v45
	global_store_dwordx4 v[168:169], v[164:167], off
	v_pk_mul_f32 v[36:37], v[36:37], vcc op_sel_hi:[1,0]
	v_pk_mul_f32 v[34:35], v[34:35], vcc op_sel_hi:[1,0]
	v_pk_mul_f32 v[40:41], v[40:41], vcc op_sel_hi:[1,0]
	v_pk_mul_f32 v[38:39], v[38:39], vcc op_sel_hi:[1,0]
	v_cvt_pk_bf16_f32 v164, v38, v39
	v_cvt_pk_bf16_f32 v165, v40, v41
	v_cvt_pk_bf16_f32 v166, v34, v35
	v_cvt_pk_bf16_f32 v167, v36, v37
	global_store_dwordx4 v[168:169], v[164:167], off offset:256
	v_pk_mul_f32 v[28:29], v[28:29], vcc op_sel_hi:[1,0]
	v_pk_mul_f32 v[26:27], v[26:27], vcc op_sel_hi:[1,0]
	v_add_u32_e32 v164, 0xa0, v163
	v_mad_i64_i32 v[164:165], s[18:19], v164, s27, v[156:157]
	v_lshl_add_u64 v[168:169], v[164:165], 0, v[158:159]
	v_pk_mul_f32 v[32:33], v[32:33], vcc op_sel_hi:[1,0]
	v_pk_mul_f32 v[30:31], v[30:31], vcc op_sel_hi:[1,0]
	v_cvt_pk_bf16_f32 v164, v30, v31
	v_cvt_pk_bf16_f32 v165, v32, v33
	v_cvt_pk_bf16_f32 v166, v26, v27
	v_cvt_pk_bf16_f32 v167, v28, v29
	global_store_dwordx4 v[168:169], v[164:167], off
	v_pk_mul_f32 v[20:21], v[20:21], vcc op_sel_hi:[1,0]
	v_pk_mul_f32 v[18:19], v[18:19], vcc op_sel_hi:[1,0]
	v_pk_mul_f32 v[24:25], v[24:25], vcc op_sel_hi:[1,0]
	v_pk_mul_f32 v[22:23], v[22:23], vcc op_sel_hi:[1,0]
	v_add_u32_e32 v163, 0xb0, v163
	v_cvt_pk_bf16_f32 v164, v22, v23
	v_cvt_pk_bf16_f32 v165, v24, v25
	v_cvt_pk_bf16_f32 v166, v18, v19
	v_cvt_pk_bf16_f32 v167, v20, v21
	v_mad_i64_i32 v[156:157], s[18:19], v163, s27, v[156:157]
	global_store_dwordx4 v[168:169], v[164:167], off offset:256
	v_pk_mul_f32 v[10:11], v[10:11], vcc op_sel_hi:[1,0]
	s_nop 0
	v_lshl_add_u64 v[164:165], v[156:157], 0, v[158:159]
	v_pk_mul_f32 v[16:17], v[16:17], vcc op_sel_hi:[1,0]
	v_pk_mul_f32 v[14:15], v[14:15], vcc op_sel_hi:[1,0]
	v_pk_mul_f32 v[12:13], v[12:13], vcc op_sel_hi:[1,0]
	v_cvt_pk_bf16_f32 v156, v14, v15
	v_cvt_pk_bf16_f32 v157, v16, v17
	v_cvt_pk_bf16_f32 v158, v10, v11
	v_cvt_pk_bf16_f32 v159, v12, v13
	global_store_dwordx4 v[164:165], v[156:159], off
	v_pk_mul_f32 v[4:5], v[4:5], vcc op_sel_hi:[1,0]
	v_pk_mul_f32 v[2:3], v[2:3], vcc op_sel_hi:[1,0]
	v_pk_mul_f32 v[8:9], v[8:9], vcc op_sel_hi:[1,0]
	v_pk_mul_f32 v[6:7], v[6:7], vcc op_sel_hi:[1,0]
	v_cvt_pk_bf16_f32 v156, v6, v7
	v_cvt_pk_bf16_f32 v157, v8, v9
	v_cvt_pk_bf16_f32 v158, v2, v3
	v_cvt_pk_bf16_f32 v159, v4, v5
	global_store_dwordx4 v[164:165], v[156:159], off offset:256
	s_cbranch_execnz .LBB0_285
